# v65 + NA-latent loop K/V prefetch with two register sets (no register copies), placement-compensated
# speedup vs baseline: 1.0078x; 1.0030x over previous
.Ldl_ctxaddr:
	s_sub_i32 s20, s3, 63
	s_lshl_b64 s[4:5], s[20:21], 15
	v_lshl_add_u64 v[66:67], v[172:173], 0, s[4:5]
	s_branch .LBB0_232
	s_nop 0
	s_nop 0
	s_nop 0
	s_nop 0
	s_nop 0
	s_nop 0
	s_nop 0
	s_nop 0
	s_nop 0
	s_nop 0
	s_nop 0
	s_nop 0
	s_nop 0
	s_nop 0
	s_nop 0
	s_nop 0
	s_nop 0
	s_nop 0
	s_nop 0
	s_nop 0
	s_nop 0
	s_nop 0
	s_nop 0
	s_nop 0
	s_nop 0
	s_nop 0
	s_nop 0
	s_nop 0
	s_nop 0
	s_nop 0
	s_nop 0
	s_nop 0
